# barrier: the XCD's last arriver no longer waits for the ack of its release atomic before the workgroup barrier
# speedup vs baseline: 1.0129x; 1.0129x over previous
.LBB0_139:
	s_or_b64 exec, exec, s[8:9]
.LBB0_140:
	s_or_b64 exec, exec, s[0:1]
	v_readlane_b32 s4, v255, 18
	v_readlane_b32 s5, v255, 19
	s_mov_b32 s0, 1
	s_mov_b64 s[6:7], 0
	s_and_b64 vcc, exec, s[4:5]
	s_waitcnt lgkmcnt(0)
	s_barrier
	s_cbranch_vccnz .LBB0_549

.LBB0_229:
	s_or_b64 exec, exec, s[10:11]
.LBB0_230:
	s_or_b64 exec, exec, s[0:1]
	v_readlane_b32 s56, v253, 32
	s_xor_b64 s[0:1], s[6:7], -1
	v_readlane_b32 s70, v253, 46
	v_readlane_b32 s71, v253, 47
	v_writelane_b32 v255, s0, 18
	s_mov_b64 s[6:7], s[70:71]
	s_waitcnt lgkmcnt(0)
	v_writelane_b32 v255, s1, 19
	s_barrier
	s_add_u32 s8, s6, 0x12d00000
	v_mov_b32_e32 v24, v218
	s_movk_i32 s0, 0x100
	s_addc_u32 s9, s7, 0
	s_and_b32 s98, s2, 7
	s_mul_i32 s98, s98, 0xe00000
	s_add_u32 s8, s8, s98
	s_addc_u32 s9, s9, 0
	v_readlane_b32 s57, v253, 33
	v_cmp_gt_i32_e32 vcc, s0, v24
	v_readlane_b32 s58, v253, 34
	v_readlane_b32 s59, v253, 35
	v_readlane_b32 s60, v253, 36
	v_readlane_b32 s61, v253, 37
	v_readlane_b32 s62, v253, 38
	v_readlane_b32 s63, v253, 39
	v_readlane_b32 s64, v253, 40
	v_readlane_b32 s65, v253, 41
	v_readlane_b32 s66, v253, 42
	v_readlane_b32 s67, v253, 43
	v_readlane_b32 s68, v253, 44
	v_readlane_b32 s69, v253, 45
	s_and_saveexec_b64 s[0:1], vcc
	s_xor_b64 s[0:1], exec, s[0:1]
	s_cbranch_execz .LBB0_243
	v_lshlrev_b32_e32 v0, 3, v24
	v_and_b32_e32 v32, 0x3f8, v0
	v_lshlrev_b32_e32 v20, 2, v32
	global_load_dwordx4 v[0:3], v20, s[22:23] offset:16
	global_load_dwordx4 v[4:7], v20, s[22:23]
	global_load_dwordx4 v[8:11], v20, s[20:21] offset:16
	global_load_dwordx4 v[12:15], v20, s[20:21]
	global_load_dwordx4 v[16:19], v20, s[18:19] offset:16
	s_nop 0
	global_load_dwordx4 v[20:23], v20, s[18:19]
	s_add_u32 s12, s6, 0xa900000
	s_addc_u32 s13, s7, 0
	s_add_u32 s18, s6, 0xe900000
	s_addc_u32 s19, s7, 0
	v_ashrrev_i32_e32 v33, 7, v24
	s_mov_b64 s[20:21], s[2:3]
	s_branch .LBB0_234

.LBB0_379:
	s_or_b64 exec, exec, s[8:9]
.LBB0_380:
	s_or_b64 exec, exec, s[0:1]
	v_readlane_b32 s56, v253, 32
	v_readlane_b32 s57, v253, 33
	v_readlane_b32 s70, v253, 46
	v_readlane_b32 s71, v253, 47
	v_readlane_b32 s4, v254, 36
	s_mov_b64 s[0:1], s[70:71]
	s_movk_i32 s20, 0x400
	s_waitcnt vmcnt(2)
	v_mov_b32_e32 v12, v218
	v_readlane_b32 s5, v254, 37
	v_readlane_b32 s50, v254, 57
	v_readlane_b32 s56, v254, 59
	s_waitcnt lgkmcnt(0)
	s_barrier
	s_and_b64 vcc, exec, s[4:5]
	v_readfirstlane_b32 s10, v12
	v_readlane_b32 s51, v254, 58
	v_readlane_b32 s57, v254, 60
	v_readlane_b32 s58, v253, 34
	v_readlane_b32 s59, v253, 35
	v_readlane_b32 s60, v253, 36
	v_readlane_b32 s61, v253, 37
	v_readlane_b32 s62, v253, 38
	v_readlane_b32 s63, v253, 39
	v_readlane_b32 s64, v253, 40
	v_readlane_b32 s65, v253, 41
	v_readlane_b32 s66, v253, 42
	v_readlane_b32 s67, v253, 43
	v_readlane_b32 s68, v253, 44
	v_readlane_b32 s69, v253, 45
	s_cbranch_vccz .LBB0_405
	v_lshlrev_b32_e32 v0, 4, v12
	v_add_u32_e32 v1, 0x2000, v0
	v_ashrrev_i32_e32 v2, 31, v1
	v_lshrrev_b32_e32 v2, 22, v2
	v_add_u32_e32 v2, v1, v2
	v_ashrrev_i32_e32 v2, 10, v2
	v_mul_i32_i24_e32 v3, 0x400, v2
	v_sub_u32_e32 v1, v1, v3
	v_lshrrev_b32_e32 v3, 4, v1
	v_bitop3_b32 v1, v3, v1, 32 bitop3:0x6c
	v_ashrrev_i32_e32 v3, 31, v1
	s_add_u32 s16, s0, 0xc00000
	v_lshrrev_b32_e32 v3, 26, v3
	s_addc_u32 s33, s1, 0
	v_add_u32_e32 v3, v1, v3
	v_lshlrev_b32_e32 v5, 3, v2
	s_add_u32 s4, s0, s52
	v_ashrrev_i32_e32 v4, 6, v3
	v_and_b32_e32 v5, -16, v5
	v_lshlrev_b32_e32 v2, 5, v2
	s_addc_u32 s5, s1, 0
	v_add_u32_e32 v5, v4, v5
	v_and_b32_e32 v13, 32, v2
	v_and_b32_e32 v2, 0xc0, v3
	s_add_u32 s34, s4, 0x5400000
	v_and_b32_e32 v4, 3, v4
	s_mov_b32 s4, 0x7fffffe0
	v_lshrrev_b32_e32 v6, 2, v5
	v_lshlrev_b32_e32 v7, 1, v5
	v_sub_u32_e32 v1, v1, v2
	v_and_or_b32 v4, v5, s4, v4
	v_and_b32_e32 v6, 4, v6
	v_and_b32_e32 v7, 24, v7
	v_ashrrev_i16_sdwa v1, v221, sext(v1) dst_sel:DWORD dst_unused:UNUSED_PAD src0_sel:DWORD src1_sel:BYTE_0
	v_or3_b32 v4, v4, v6, v7
	v_bfe_i32 v14, v1, 0, 16
	v_mul_lo_u32 v4, v4, s20
	v_add_u32_e32 v1, v13, v14
	v_mul_lo_u32 v15, v5, s20
	v_add_lshl_u32 v132, v4, v1, 1
	v_add_lshl_u32 v134, v1, v15, 1
	v_bfe_i32 v1, v12, 27, 1
	v_lshrrev_b32_e32 v1, 22, v1
	v_add_u32_e32 v1, v0, v1
	v_and_b32_e32 v1, 0xfffffc00, v1
	v_sub_u32_e32 v0, v0, v1
	v_lshrrev_b32_e32 v1, 4, v0
	v_ashrrev_i32_e32 v3, 31, v12
	v_bitop3_b32 v0, v1, v0, 32 bitop3:0x6c
	v_lshrrev_b32_e32 v3, 26, v3
	v_ashrrev_i32_e32 v1, 31, v0
	v_add_u32_e32 v3, v12, v3
	v_lshrrev_b32_e32 v1, 26, v1
	v_ashrrev_i32_e32 v3, 6, v3
	v_add_u32_e32 v1, v0, v1
	v_lshlrev_b32_e32 v4, 3, v3
	v_ashrrev_i32_e32 v2, 6, v1
	v_and_b32_e32 v4, -16, v4
	s_addc_u32 s35, s5, 0
	s_ashr_i32 s21, s20, 31
	v_add_u32_e32 v4, v2, v4
	v_and_b32_e32 v2, 3, v2
	s_lshl_b64 s[8:9], s[20:21], 9
	v_and_or_b32 v2, v4, s4, v2
	v_readlane_b32 s4, v254, 52
	v_readlane_b32 s13, v255, 6
	s_mul_i32 s4, s8, s4
	s_mul_hi_u32 s5, s8, s13
	s_add_i32 s12, s5, s4
	s_lshr_b64 s[4:5], s[20:21], 23
	v_readlane_b32 s24, v254, 47
	s_mul_i32 s5, s4, s13
	v_readlane_b32 s25, v254, 48
	v_and_b32_e32 v1, 0xc0, v1
	s_add_i32 s12, s12, s5
	s_mul_i32 s5, s8, s25
	s_mul_hi_u32 s18, s8, s24
	s_ashr_i32 s22, s10, 6
	v_lshrrev_b32_e32 v5, 2, v4
	v_lshlrev_b32_e32 v6, 1, v4
	v_sub_u32_e32 v0, v0, v1
	s_add_i32 s5, s18, s5
	s_mul_i32 s4, s4, s24
	s_ashr_i32 s11, s10, 8
	s_lshl_b64 s[6:7], s[20:21], 8
	s_lshl_b32 s36, s22, 10
	v_and_b32_e32 v5, 4, v5
	v_and_b32_e32 v6, 24, v6
	v_lshlrev_b32_e32 v3, 5, v3
	v_ashrrev_i16_sdwa v0, v221, sext(v0) dst_sel:DWORD dst_unused:UNUSED_PAD src0_sel:DWORD src1_sel:BYTE_0
	s_add_i32 s5, s5, s4
	s_mul_i32 s4, s8, s24
	v_or3_b32 v2, v2, v5, v6
	s_waitcnt vmcnt(1)
	v_and_b32_e32 v16, 32, v3
	v_bfe_i32 v17, v0, 0, 16
	s_add_u32 s30, s34, s4
	v_mul_lo_u32 v2, v2, s20
	v_add_u32_e32 v0, v16, v17
	s_addc_u32 s31, s35, s5
	s_add_i32 s37, s36, 0
	v_add_lshl_u32 v176, v2, v0, 1
	s_add_i32 m0, s37, 0x10000
	s_mul_i32 s13, s8, s13
	global_load_lds_dwordx4 v176, s[30:31]
	s_add_i32 m0, s37, 0x12000
	s_add_u32 s4, s30, s6
	global_load_lds_dwordx4 v132, s[30:31]
	s_addc_u32 s5, s31, s7
	s_add_i32 m0, s37, 0x14000
	v_mul_lo_u32 v18, v4, s20
	global_load_lds_dwordx4 v176, s[4:5]
	s_add_i32 m0, s37, 0x16000
	s_add_u32 s28, s16, s13
	v_mov_b32_e32 v133, v177
	s_addc_u32 s29, s33, s12
	s_add_i32 s38, s37, 0x2000
	v_add_lshl_u32 v136, v0, v18, 1
	v_lshl_add_u64 v[4:5], s[4:5], 0, v[176:177]
	v_lshl_add_u64 v[6:7], s[4:5], 0, v[132:133]
	global_load_lds_dwordx4 v132, s[4:5]
	s_mov_b32 m0, s37
	s_add_u32 s4, s28, s6
	global_load_lds_dwordx4 v136, s[28:29]
	s_mov_b32 m0, s38
	s_addc_u32 s5, s29, s7
	s_add_i32 s39, s37, 0x4000
	global_load_lds_dwordx4 v134, s[28:29]
	s_mov_b32 m0, s39
	s_add_i32 s48, s37, 0x6000
	global_load_lds_dwordx4 v136, s[4:5]
	s_mov_b32 m0, s48
	v_mov_b32_e32 v137, v177
	global_load_lds_dwordx4 v134, s[4:5]
	v_mov_b32_e32 v135, v177
	s_cmp_eq_u32 s11, 1
	v_lshl_add_u64 v[0:1], s[30:31], 0, v[176:177]
	v_lshl_add_u64 v[2:3], s[30:31], 0, v[132:133]
	v_lshl_add_u64 v[8:9], s[28:29], 0, v[136:137]
	v_lshl_add_u64 v[10:11], s[28:29], 0, v[134:135]
	s_cselect_b64 s[12:13], -1, 0
	s_cmp_lg_u32 s11, 1
	s_cbranch_scc1 .LBB0_383
	s_barrier

.LBB0_456:
	s_or_b64 exec, exec, s[8:9]
.LBB0_457:
	s_or_b64 exec, exec, s[0:1]
	v_readlane_b32 s56, v253, 32
	v_readlane_b32 s68, v253, 44
	v_readlane_b32 s69, v253, 45
	v_readlane_b32 s70, v253, 46
	v_readlane_b32 s71, v253, 47
	v_readlane_b32 s4, v253, 50
	s_mov_b64 s[0:1], s[70:71]
	s_movk_i32 s20, 0xb00
	v_mov_b32_e32 v18, v218
	v_readlane_b32 s5, v253, 51
	v_readlane_b32 s68, v254, 57
	v_readlane_b32 s70, v254, 59
	s_waitcnt lgkmcnt(0)
	s_barrier
	s_and_b64 vcc, exec, s[4:5]
	v_readfirstlane_b32 s10, v18
	v_readlane_b32 s69, v254, 58
	v_readlane_b32 s71, v254, 60
	v_readlane_b32 s57, v253, 33
	v_readlane_b32 s58, v253, 34
	v_readlane_b32 s59, v253, 35
	v_readlane_b32 s60, v253, 36
	v_readlane_b32 s61, v253, 37
	v_readlane_b32 s62, v253, 38
	v_readlane_b32 s63, v253, 39
	v_readlane_b32 s64, v253, 40
	v_readlane_b32 s65, v253, 41
	v_readlane_b32 s66, v253, 42
	v_readlane_b32 s67, v253, 43
	s_cbranch_vccz .LBB0_498
	v_lshlrev_b32_e32 v0, 4, v18
	v_add_u32_e32 v1, 0x2000, v0
	v_ashrrev_i32_e32 v2, 31, v1
	v_lshrrev_b32_e32 v2, 22, v2
	v_add_u32_e32 v2, v1, v2
	v_ashrrev_i32_e32 v2, 10, v2
	v_mul_i32_i24_e32 v3, 0x400, v2
	v_sub_u32_e32 v1, v1, v3
	v_lshrrev_b32_e32 v3, 4, v1
	v_bitop3_b32 v1, v3, v1, 32 bitop3:0x6c
	v_ashrrev_i32_e32 v3, 31, v1
	s_add_u32 s33, s0, 0x12d00000
	v_lshrrev_b32_e32 v3, 26, v3
	s_addc_u32 s34, s1, 0
	v_add_u32_e32 v3, v1, v3
	v_lshlrev_b32_e32 v5, 3, v2
	s_add_u32 s4, s0, s52
	v_ashrrev_i32_e32 v4, 6, v3
	v_and_b32_e32 v5, -16, v5
	v_lshlrev_b32_e32 v2, 5, v2
	s_addc_u32 s5, s1, 0
	v_add_u32_e32 v5, v4, v5
	v_and_b32_e32 v12, 32, v2
	v_and_b32_e32 v2, 0xc0, v3
	s_add_u32 s35, s4, 0x5f00000
	v_and_b32_e32 v4, 3, v4
	s_mov_b32 s4, 0x7fffffe0
	v_lshrrev_b32_e32 v6, 2, v5
	v_lshlrev_b32_e32 v7, 1, v5
	v_sub_u32_e32 v1, v1, v2
	v_and_or_b32 v4, v5, s4, v4
	v_and_b32_e32 v6, 4, v6
	v_and_b32_e32 v7, 24, v7
	v_ashrrev_i16_sdwa v1, v221, sext(v1) dst_sel:DWORD dst_unused:UNUSED_PAD src0_sel:DWORD src1_sel:BYTE_0
	v_or3_b32 v4, v4, v6, v7
	v_bfe_i32 v13, v1, 0, 16
	v_mul_lo_u32 v4, v4, s20
	v_add_u32_e32 v1, v12, v13
	v_mul_lo_u32 v14, v5, s20
	v_add_lshl_u32 v156, v4, v1, 1
	v_add_lshl_u32 v158, v1, v14, 1
	v_bfe_i32 v1, v18, 27, 1
	v_lshrrev_b32_e32 v1, 22, v1
	v_add_u32_e32 v1, v0, v1
	v_and_b32_e32 v1, 0xfffffc00, v1
	v_sub_u32_e32 v0, v0, v1
	v_lshrrev_b32_e32 v1, 4, v0
	v_ashrrev_i32_e32 v3, 31, v18
	v_bitop3_b32 v0, v1, v0, 32 bitop3:0x6c
	v_lshrrev_b32_e32 v3, 26, v3
	v_ashrrev_i32_e32 v1, 31, v0
	v_add_u32_e32 v3, v18, v3
	v_lshrrev_b32_e32 v1, 26, v1
	v_ashrrev_i32_e32 v3, 6, v3
	v_add_u32_e32 v1, v0, v1
	v_lshlrev_b32_e32 v4, 3, v3
	v_ashrrev_i32_e32 v2, 6, v1
	v_and_b32_e32 v4, -16, v4
	s_addc_u32 s36, s5, 0
	s_ashr_i32 s21, s20, 31
	v_add_u32_e32 v4, v2, v4
	v_and_b32_e32 v2, 3, v2
	s_lshl_b64 s[8:9], s[20:21], 9
	v_and_or_b32 v2, v4, s4, v2
	v_readlane_b32 s4, v254, 53
	s_mul_i32 s4, s8, s4
	s_mul_hi_u32 s5, s8, s95
	s_add_i32 s12, s5, s4
	s_lshr_b64 s[4:5], s[20:21], 23
	v_readlane_b32 s22, v254, 50
	s_mul_i32 s5, s4, s95
	v_readlane_b32 s23, v254, 51
	v_and_b32_e32 v1, 0xc0, v1
	s_add_i32 s12, s12, s5
	s_mul_i32 s5, s8, s23
	s_mul_hi_u32 s18, s8, s22
	s_ashr_i32 s16, s10, 6
	v_lshrrev_b32_e32 v5, 2, v4
	v_lshlrev_b32_e32 v6, 1, v4
	v_sub_u32_e32 v0, v0, v1
	s_add_i32 s5, s18, s5
	s_mul_i32 s4, s4, s22
	s_ashr_i32 s11, s10, 8
	s_lshl_b64 s[6:7], s[20:21], 8
	s_lshl_b32 s37, s16, 10
	v_and_b32_e32 v5, 4, v5
	v_and_b32_e32 v6, 24, v6
	v_lshlrev_b32_e32 v3, 5, v3
	v_ashrrev_i16_sdwa v0, v221, sext(v0) dst_sel:DWORD dst_unused:UNUSED_PAD src0_sel:DWORD src1_sel:BYTE_0
	s_add_i32 s5, s5, s4
	s_mul_i32 s4, s8, s22
	v_or3_b32 v2, v2, v5, v6
	v_and_b32_e32 v15, 32, v3
	v_bfe_i32 v16, v0, 0, 16
	s_add_u32 s30, s35, s4
	v_mul_lo_u32 v2, v2, s20
	v_add_u32_e32 v0, v15, v16
	s_addc_u32 s31, s36, s5
	s_add_i32 s38, s37, 0
	v_add_lshl_u32 v176, v2, v0, 1
	s_add_i32 m0, s38, 0x10000
	s_mul_i32 s13, s8, s95
	global_load_lds_dwordx4 v176, s[30:31]
	s_add_i32 m0, s38, 0x12000
	s_add_u32 s4, s30, s6
	global_load_lds_dwordx4 v156, s[30:31]
	s_addc_u32 s5, s31, s7
	s_add_i32 m0, s38, 0x14000
	v_mul_lo_u32 v17, v4, s20
	global_load_lds_dwordx4 v176, s[4:5]
	s_add_i32 m0, s38, 0x16000
	s_add_u32 s28, s33, s13
	v_mov_b32_e32 v157, v177
	s_addc_u32 s29, s34, s12
	s_add_i32 s39, s38, 0x2000
	v_add_lshl_u32 v160, v0, v17, 1
	v_lshl_add_u64 v[4:5], s[4:5], 0, v[176:177]
	v_lshl_add_u64 v[6:7], s[4:5], 0, v[156:157]
	global_load_lds_dwordx4 v156, s[4:5]
	s_mov_b32 m0, s38
	s_add_u32 s4, s28, s6
	global_load_lds_dwordx4 v160, s[28:29]
	s_mov_b32 m0, s39
	s_addc_u32 s5, s29, s7
	s_add_i32 s48, s38, 0x4000
	global_load_lds_dwordx4 v158, s[28:29]
	s_mov_b32 m0, s48
	s_add_i32 s49, s38, 0x6000
	global_load_lds_dwordx4 v160, s[4:5]
	s_mov_b32 m0, s49
	v_mov_b32_e32 v161, v177
	global_load_lds_dwordx4 v158, s[4:5]
	v_mov_b32_e32 v159, v177
	s_cmp_eq_u32 s11, 1
	v_lshl_add_u64 v[0:1], s[30:31], 0, v[176:177]
	v_lshl_add_u64 v[2:3], s[30:31], 0, v[156:157]
	v_lshl_add_u64 v[8:9], s[28:29], 0, v[160:161]
	v_lshl_add_u64 v[10:11], s[28:29], 0, v[158:159]
	s_cselect_b64 s[12:13], -1, 0
	s_cmp_lg_u32 s11, 1
	s_cbranch_scc1 .LBB0_460
	s_barrier

.LBB0_550:
	s_or_b64 exec, exec, s[8:9]
.LBB0_551:
	s_or_b64 exec, exec, s[0:1]
	s_mov_b64 s[0:1], 1
	v_writelane_b32 v253, s0, 54
	s_mov_b64 s[40:41], 0
	s_waitcnt lgkmcnt(0)
	v_writelane_b32 v253, s1, 55
	s_barrier
	v_readlane_b32 s0, v253, 52
	v_readlane_b32 s1, v253, 53
	s_and_b64 vcc, exec, s[0:1]
	s_cbranch_vccnz .LBB0_1299

.LBB0_778:
	s_or_b64 exec, exec, s[8:9]
.LBB0_779:
	s_or_b64 exec, exec, s[0:1]
	s_andn2_b64 vcc, exec, s[40:41]
	s_waitcnt lgkmcnt(0)
	s_barrier
	s_cbranch_vccnz .LBB0_830
	v_readlane_b32 s16, v253, 32
	v_readlane_b32 s18, v253, 34
	v_readlane_b32 s19, v253, 35
	v_readlane_b32 s20, v253, 36
	v_readlane_b32 s30, v253, 46
	v_readlane_b32 s31, v253, 47
	v_readlane_b32 s0, v255, 20
	s_mov_b64 s[18:19], s[30:31]
	s_movk_i32 s20, 0x100
	v_mov_b32_e32 v12, v218
	v_readlane_b32 s1, v255, 21
	s_and_b64 vcc, exec, s[0:1]
	v_readfirstlane_b32 s10, v12
	v_readlane_b32 s17, v253, 33
	v_readlane_b32 s21, v253, 37
	v_readlane_b32 s22, v253, 38
	v_readlane_b32 s23, v253, 39
	v_readlane_b32 s24, v253, 40
	v_readlane_b32 s25, v253, 41
	v_readlane_b32 s26, v253, 42
	v_readlane_b32 s27, v253, 43
	v_readlane_b32 s28, v253, 44
	v_readlane_b32 s29, v253, 45
	s_cbranch_vccnz .LBB0_805
	v_lshlrev_b32_e32 v0, 4, v12
	v_add_u32_e32 v1, 0x2000, v0
	v_ashrrev_i32_e32 v2, 31, v1
	v_lshrrev_b32_e32 v2, 22, v2
	v_add_u32_e32 v2, v1, v2
	v_ashrrev_i32_e32 v2, 10, v2
	v_mul_i32_i24_e32 v3, 0x400, v2
	v_sub_u32_e32 v1, v1, v3
	v_lshrrev_b32_e32 v3, 4, v1
	v_bitop3_b32 v1, v3, v1, 32 bitop3:0x6c
	v_ashrrev_i32_e32 v3, 31, v1
	v_lshrrev_b32_e32 v3, 26, v3
	v_add_u32_e32 v3, v1, v3
	v_lshlrev_b32_e32 v5, 3, v2
	v_ashrrev_i32_e32 v4, 6, v3
	v_and_b32_e32 v5, -16, v5
	v_lshlrev_b32_e32 v2, 5, v2
	v_add_u32_e32 v5, v4, v5
	v_and_b32_e32 v13, 32, v2
	v_and_b32_e32 v2, 0xc0, v3
	v_and_b32_e32 v4, 3, v4
	s_mov_b32 s8, 0x7fffffe0
	v_lshrrev_b32_e32 v6, 2, v5
	v_lshlrev_b32_e32 v7, 1, v5
	v_sub_u32_e32 v1, v1, v2
	v_and_or_b32 v4, v5, s8, v4
	v_and_b32_e32 v6, 4, v6
	v_and_b32_e32 v7, 24, v7
	v_ashrrev_i16_sdwa v1, v205, sext(v1) dst_sel:DWORD dst_unused:UNUSED_PAD src0_sel:DWORD src1_sel:BYTE_0
	v_or3_b32 v4, v4, v6, v7
	v_bfe_i32 v14, v1, 0, 16
	v_mul_lo_u32 v4, v4, s20
	v_add_u32_e32 v1, v13, v14
	v_mul_lo_u32 v15, v5, s20
	v_add_lshl_u32 v128, v4, v1, 1
	v_add_lshl_u32 v130, v1, v15, 1
	v_bfe_i32 v1, v12, 27, 1
	v_lshrrev_b32_e32 v1, 22, v1
	v_add_u32_e32 v1, v0, v1
	v_and_b32_e32 v1, 0xfffffc00, v1
	v_sub_u32_e32 v0, v0, v1
	v_lshrrev_b32_e32 v1, 4, v0
	v_ashrrev_i32_e32 v3, 31, v12
	v_bitop3_b32 v0, v1, v0, 32 bitop3:0x6c
	v_lshrrev_b32_e32 v3, 26, v3
	v_ashrrev_i32_e32 v1, 31, v0
	v_add_u32_e32 v3, v12, v3
	s_add_u32 s4, s18, 0x13900000
	v_lshrrev_b32_e32 v1, 26, v1
	v_ashrrev_i32_e32 v3, 6, v3
	s_addc_u32 s33, s19, 0
	s_and_b32 s98, s2, 7
	s_mul_i32 s98, s98, 0x1400000
	s_add_u32 s4, s4, s98
	s_addc_u32 s33, s33, 0
	v_add_u32_e32 v1, v0, v1
	v_lshlrev_b32_e32 v4, 3, v3
	s_add_u32 s34, s18, 0x7f00000
	v_ashrrev_i32_e32 v2, 6, v1
	v_and_b32_e32 v4, -16, v4
	s_addc_u32 s35, s19, 0
	s_ashr_i32 s21, s20, 31
	v_add_u32_e32 v4, v2, v4
	v_and_b32_e32 v2, 3, v2
	s_lshl_b64 s[6:7], s[20:21], 9
	v_and_or_b32 v2, v4, s8, v2
	v_readlane_b32 s8, v254, 53
	s_mul_i32 s8, s6, s8
	s_mul_hi_u32 s9, s6, s95
	s_add_i32 s14, s9, s8
	s_lshr_b64 s[8:9], s[20:21], 23
	v_readlane_b32 s24, v254, 50
	s_mul_i32 s9, s8, s95
	v_readlane_b32 s25, v254, 51
	v_and_b32_e32 v1, 0xc0, v1
	s_add_i32 s14, s14, s9
	s_mul_i32 s9, s6, s25
	s_mul_hi_u32 s16, s6, s24
	s_ashr_i32 s11, s10, 6
	v_lshrrev_b32_e32 v5, 2, v4
	v_lshlrev_b32_e32 v6, 1, v4
	v_sub_u32_e32 v0, v0, v1
	s_add_i32 s9, s16, s9
	s_mul_i32 s8, s8, s24
	s_ashr_i32 s22, s10, 8
	s_lshl_b64 s[0:1], s[20:21], 8
	s_lshl_b32 s36, s11, 10
	v_and_b32_e32 v5, 4, v5
	v_and_b32_e32 v6, 24, v6
	v_lshlrev_b32_e32 v3, 5, v3
	v_ashrrev_i16_sdwa v0, v205, sext(v0) dst_sel:DWORD dst_unused:UNUSED_PAD src0_sel:DWORD src1_sel:BYTE_0
	s_add_i32 s9, s9, s8
	s_mul_i32 s8, s6, s24
	v_or3_b32 v2, v2, v5, v6
	v_and_b32_e32 v16, 32, v3
	v_bfe_i32 v17, v0, 0, 16
	s_add_u32 s30, s34, s8
	v_mul_lo_u32 v2, v2, s20
	v_add_u32_e32 v0, v16, v17
	s_addc_u32 s31, s35, s9
	s_add_i32 s37, s36, 0
	v_add_lshl_u32 v132, v2, v0, 1
	s_add_i32 m0, s37, 0x10000
	s_mul_i32 s15, s6, s95
	global_load_lds_dwordx4 v132, s[30:31]
	s_add_i32 m0, s37, 0x12000
	s_add_u32 s8, s30, s0
	global_load_lds_dwordx4 v128, s[30:31]
	s_addc_u32 s9, s31, s1
	s_add_i32 m0, s37, 0x14000
	v_mul_lo_u32 v18, v4, s20
	global_load_lds_dwordx4 v132, s[8:9]
	s_add_i32 m0, s37, 0x16000
	s_add_u32 s16, s4, s15
	v_mov_b32_e32 v133, v181
	v_mov_b32_e32 v129, v181
	s_addc_u32 s17, s33, s14
	s_add_i32 s38, s37, 0x2000
	v_add_lshl_u32 v134, v0, v18, 1
	v_lshl_add_u64 v[4:5], s[8:9], 0, v[132:133]
	v_lshl_add_u64 v[6:7], s[8:9], 0, v[128:129]
	global_load_lds_dwordx4 v128, s[8:9]
	s_mov_b32 m0, s37
	s_add_u32 s8, s16, s0
	global_load_lds_dwordx4 v134, s[16:17]
	s_mov_b32 m0, s38
	s_addc_u32 s9, s17, s1
	s_add_i32 s39, s37, 0x4000
	global_load_lds_dwordx4 v130, s[16:17]
	s_mov_b32 m0, s39
	s_add_i32 s44, s37, 0x6000
	global_load_lds_dwordx4 v134, s[8:9]
	s_mov_b32 m0, s44
	v_mov_b32_e32 v135, v181
	global_load_lds_dwordx4 v130, s[8:9]
	v_mov_b32_e32 v131, v181
	s_cmp_eq_u32 s22, 1
	v_lshl_add_u64 v[0:1], s[30:31], 0, v[132:133]
	v_lshl_add_u64 v[2:3], s[30:31], 0, v[128:129]
	v_lshl_add_u64 v[8:9], s[16:17], 0, v[134:135]
	v_lshl_add_u64 v[10:11], s[16:17], 0, v[130:131]
	s_cselect_b64 s[8:9], -1, 0
	s_cmp_lg_u32 s22, 1
	s_cbranch_scc1 .LBB0_783
	s_barrier

.LBB0_934:
	s_or_b64 exec, exec, s[8:9]
.LBB0_935:
	s_or_b64 exec, exec, s[0:1]
	v_readlane_b32 s16, v253, 32
	v_readlane_b32 s0, v254, 42
	v_readlane_b32 s30, v253, 46
	v_readlane_b32 s31, v253, 47
	v_readlane_b32 s1, v254, 43
	s_mov_b64 s[6:7], s[30:31]
	s_andn2_b64 vcc, exec, s[0:1]
	s_waitcnt lgkmcnt(0)
	s_barrier
	v_readlane_b32 s17, v253, 33
	v_readlane_b32 s18, v253, 34
	v_readlane_b32 s19, v253, 35
	v_readlane_b32 s20, v253, 36
	v_readlane_b32 s21, v253, 37
	v_readlane_b32 s22, v253, 38
	v_readlane_b32 s23, v253, 39
	v_readlane_b32 s24, v253, 40
	v_readlane_b32 s25, v253, 41
	v_readlane_b32 s26, v253, 42
	v_readlane_b32 s27, v253, 43
	v_readlane_b32 s28, v253, 44
	v_readlane_b32 s29, v253, 45
	s_cbranch_vccnz .LBB0_983
	s_add_u32 s8, s6, 0x12d00000
	s_addc_u32 s9, s7, 0
	s_and_b32 s98, s2, 7
	s_mul_i32 s98, s98, 0xa00000
	s_add_u32 s8, s8, s98
	s_addc_u32 s9, s9, 0
	s_add_u32 s4, s6, 0xa900000
	s_addc_u32 s33, s7, 0
	s_add_u32 s44, s6, 0x12900000
	s_addc_u32 s45, s7, 0
	s_add_u32 s46, s6, 0xe900000
	s_addc_u32 s47, s7, 0
	s_add_u32 s14, s6, 0x13900000
	s_addc_u32 s15, s7, 0
	s_and_b32 s98, s2, 7
	s_mul_i32 s98, s98, 0xe00000
	s_add_u32 s14, s14, s98
	s_addc_u32 s15, s15, 0
	v_readlane_b32 s48, v255, 10
	s_and_b32 s100, s2, 7
	s_lshl_b32 s100, s100, 5
	s_add_i32 s48, s48, s100
	s_add_i32 s100, s48, 64
	s_branch .LBB0_938

.LBB0_1034:
	s_or_b64 exec, exec, s[8:9]
.LBB0_1035:
	s_or_b64 exec, exec, s[0:1]
	v_readlane_b32 s16, v253, 32
	v_readlane_b32 s30, v253, 46
	v_readlane_b32 s31, v253, 47
	v_readlane_b32 s6, v255, 20
	s_mov_b64 s[0:1], s[30:31]
	s_movk_i32 s16, 0x400
	v_mov_b32_e32 v18, v218
	v_readlane_b32 s7, v255, 21
	s_waitcnt lgkmcnt(0)
	s_barrier
	s_and_b64 vcc, exec, s[6:7]
	v_readfirstlane_b32 s10, v18
	v_readlane_b32 s17, v253, 33
	v_readlane_b32 s18, v253, 34
	v_readlane_b32 s19, v253, 35
	v_readlane_b32 s20, v253, 36
	v_readlane_b32 s21, v253, 37
	v_readlane_b32 s22, v253, 38
	v_readlane_b32 s23, v253, 39
	v_readlane_b32 s24, v253, 40
	v_readlane_b32 s25, v253, 41
	v_readlane_b32 s26, v253, 42
	v_readlane_b32 s27, v253, 43
	v_readlane_b32 s28, v253, 44
	v_readlane_b32 s29, v253, 45
	s_cbranch_vccnz .LBB0_1076
	v_lshlrev_b32_e32 v0, 4, v18
	v_add_u32_e32 v1, 0x2000, v0
	v_ashrrev_i32_e32 v2, 31, v1
	v_lshrrev_b32_e32 v2, 22, v2
	v_add_u32_e32 v2, v1, v2
	v_ashrrev_i32_e32 v2, 10, v2
	v_mul_i32_i24_e32 v3, 0x400, v2
	v_sub_u32_e32 v1, v1, v3
	v_lshrrev_b32_e32 v3, 4, v1
	v_bitop3_b32 v1, v3, v1, 32 bitop3:0x6c
	v_ashrrev_i32_e32 v3, 31, v1
	v_lshrrev_b32_e32 v3, 26, v3
	v_add_u32_e32 v3, v1, v3
	v_lshlrev_b32_e32 v5, 3, v2
	v_ashrrev_i32_e32 v4, 6, v3
	v_and_b32_e32 v5, -16, v5
	v_lshlrev_b32_e32 v2, 5, v2
	v_add_u32_e32 v5, v4, v5
	v_and_b32_e32 v12, 32, v2
	v_and_b32_e32 v2, 0xc0, v3
	v_and_b32_e32 v4, 3, v4
	s_mov_b32 s14, 0x7fffffe0
	v_lshrrev_b32_e32 v6, 2, v5
	v_lshlrev_b32_e32 v7, 1, v5
	v_sub_u32_e32 v1, v1, v2
	v_and_or_b32 v4, v5, s14, v4
	v_and_b32_e32 v6, 4, v6
	v_and_b32_e32 v7, 24, v7
	v_ashrrev_i16_sdwa v1, v205, sext(v1) dst_sel:DWORD dst_unused:UNUSED_PAD src0_sel:DWORD src1_sel:BYTE_0
	v_or3_b32 v4, v4, v6, v7
	v_bfe_i32 v13, v1, 0, 16
	v_mul_lo_u32 v4, v4, s16
	v_add_u32_e32 v1, v12, v13
	v_mul_lo_u32 v14, v5, s16
	v_add_lshl_u32 v156, v4, v1, 1
	v_add_lshl_u32 v158, v1, v14, 1
	v_bfe_i32 v1, v18, 27, 1
	v_lshrrev_b32_e32 v1, 22, v1
	v_add_u32_e32 v1, v0, v1
	v_and_b32_e32 v1, 0xfffffc00, v1
	v_sub_u32_e32 v0, v0, v1
	v_readlane_b32 s6, v253, 54
	v_lshrrev_b32_e32 v1, 4, v0
	v_ashrrev_i32_e32 v3, 31, v18
	s_add_u32 s4, s0, 0x13900000
	v_readlane_b32 s7, v253, 55
	v_bitop3_b32 v0, v1, v0, 32 bitop3:0x6c
	v_lshrrev_b32_e32 v3, 26, v3
	s_addc_u32 s33, s1, 0
	s_and_b32 s98, s2, 7
	s_mul_i32 s98, s98, 0xe00000
	s_add_u32 s4, s4, s98
	s_addc_u32 s33, s33, 0
	s_lshl_b64 s[6:7], s[6:7], 21
	v_ashrrev_i32_e32 v1, 31, v0
	v_add_u32_e32 v3, v18, v3
	s_add_u32 s6, s0, s6
	v_lshrrev_b32_e32 v1, 26, v1
	v_ashrrev_i32_e32 v3, 6, v3
	s_addc_u32 s7, s1, s7
	v_add_u32_e32 v1, v0, v1
	v_lshlrev_b32_e32 v4, 3, v3
	s_add_u32 s34, s6, 0x8340000
	v_ashrrev_i32_e32 v2, 6, v1
	v_and_b32_e32 v4, -16, v4
	s_addc_u32 s35, s7, 0
	s_ashr_i32 s17, s16, 31
	v_add_u32_e32 v4, v2, v4
	v_and_b32_e32 v2, 3, v2
	s_lshl_b64 s[8:9], s[16:17], 9
	v_and_or_b32 v2, v4, s14, v2
	v_readlane_b32 s14, v254, 53
	s_mul_i32 s14, s8, s14
	s_mul_hi_u32 s15, s8, s95
	s_add_i32 s18, s15, s14
	s_lshr_b64 s[14:15], s[16:17], 23
	v_readlane_b32 s22, v254, 50
	s_mul_i32 s15, s14, s95
	v_readlane_b32 s23, v254, 51
	v_and_b32_e32 v1, 0xc0, v1
	s_add_i32 s18, s18, s15
	s_mul_i32 s15, s8, s23
	s_mul_hi_u32 s21, s8, s22
	s_ashr_i32 s20, s10, 6
	v_lshrrev_b32_e32 v5, 2, v4
	v_lshlrev_b32_e32 v6, 1, v4
	v_sub_u32_e32 v0, v0, v1
	s_add_i32 s15, s21, s15
	s_mul_i32 s14, s14, s22
	s_ashr_i32 s11, s10, 8
	s_lshl_b64 s[6:7], s[16:17], 8
	s_lshl_b32 s36, s20, 10
	v_and_b32_e32 v5, 4, v5
	v_and_b32_e32 v6, 24, v6
	v_lshlrev_b32_e32 v3, 5, v3
	v_ashrrev_i16_sdwa v0, v205, sext(v0) dst_sel:DWORD dst_unused:UNUSED_PAD src0_sel:DWORD src1_sel:BYTE_0
	s_add_i32 s15, s15, s14
	s_mul_i32 s14, s8, s22
	v_or3_b32 v2, v2, v5, v6
	v_and_b32_e32 v15, 32, v3
	v_bfe_i32 v16, v0, 0, 16
	s_add_u32 s30, s34, s14
	v_mul_lo_u32 v2, v2, s16
	v_add_u32_e32 v0, v15, v16
	s_addc_u32 s31, s35, s15
	s_add_i32 s37, s36, 0
	v_add_lshl_u32 v180, v2, v0, 1
	s_add_i32 m0, s37, 0x10000
	s_mul_i32 s19, s8, s95
	global_load_lds_dwordx4 v180, s[30:31]
	s_add_i32 m0, s37, 0x12000
	s_add_u32 s14, s30, s6
	global_load_lds_dwordx4 v156, s[30:31]
	s_addc_u32 s15, s31, s7
	s_add_i32 m0, s37, 0x14000
	v_mul_lo_u32 v17, v4, s16
	global_load_lds_dwordx4 v180, s[14:15]
	s_add_i32 m0, s37, 0x16000
	s_add_u32 s28, s4, s19
	v_mov_b32_e32 v157, v181
	s_addc_u32 s29, s33, s18
	s_add_i32 s38, s37, 0x2000
	s_waitcnt vmcnt(0)
	v_add_lshl_u32 v160, v0, v17, 1
	v_lshl_add_u64 v[4:5], s[14:15], 0, v[180:181]
	v_lshl_add_u64 v[6:7], s[14:15], 0, v[156:157]
	global_load_lds_dwordx4 v156, s[14:15]
	s_mov_b32 m0, s37
	s_add_u32 s14, s28, s6
	global_load_lds_dwordx4 v160, s[28:29]
	s_mov_b32 m0, s38
	s_addc_u32 s15, s29, s7
	s_add_i32 s39, s37, 0x4000
	global_load_lds_dwordx4 v158, s[28:29]
	s_mov_b32 m0, s39
	s_add_i32 s46, s37, 0x6000
	global_load_lds_dwordx4 v160, s[14:15]
	s_mov_b32 m0, s46
	v_mov_b32_e32 v161, v181
	global_load_lds_dwordx4 v158, s[14:15]
	v_mov_b32_e32 v159, v181
	s_cmp_eq_u32 s11, 1
	v_mov_b32_e32 v240, 1
	v_lshl_add_u64 v[0:1], s[30:31], 0, v[180:181]
	v_lshl_add_u64 v[2:3], s[30:31], 0, v[156:157]
	v_lshl_add_u64 v[8:9], s[28:29], 0, v[160:161]
	v_lshl_add_u64 v[10:11], s[28:29], 0, v[158:159]
	s_cselect_b64 s[14:15], -1, 0
	s_cmp_lg_u32 s11, 1
	s_cbranch_scc1 .LBB0_1038
	s_barrier

.LBB0_1127:
	s_or_b64 exec, exec, s[8:9]
.LBB0_1128:
	s_or_b64 exec, exec, s[0:1]
	v_readlane_b32 s16, v253, 32
	v_readlane_b32 s30, v253, 46
	v_readlane_b32 s31, v253, 47
	v_readlane_b32 s6, v254, 36
	s_mov_b64 s[0:1], s[30:31]
	s_movk_i32 s16, 0x400
	v_mov_b32_e32 v12, v218
	v_readlane_b32 s7, v254, 37
	s_waitcnt lgkmcnt(0)
	s_barrier
	s_andn2_b64 vcc, exec, s[6:7]
	v_readfirstlane_b32 s10, v12
	v_readlane_b32 s17, v253, 33
	v_readlane_b32 s18, v253, 34
	v_readlane_b32 s19, v253, 35
	v_readlane_b32 s20, v253, 36
	v_readlane_b32 s21, v253, 37
	v_readlane_b32 s22, v253, 38
	v_readlane_b32 s23, v253, 39
	v_readlane_b32 s24, v253, 40
	v_readlane_b32 s25, v253, 41
	v_readlane_b32 s26, v253, 42
	v_readlane_b32 s27, v253, 43
	v_readlane_b32 s28, v253, 44
	v_readlane_b32 s29, v253, 45
	s_cbranch_vccnz .LBB0_1154
	v_lshlrev_b32_e32 v0, 4, v12
	v_add_u32_e32 v1, 0x2000, v0
	v_ashrrev_i32_e32 v2, 31, v1
	v_lshrrev_b32_e32 v2, 22, v2
	v_add_u32_e32 v2, v1, v2
	v_ashrrev_i32_e32 v2, 10, v2
	v_mul_i32_i24_e32 v3, 0x400, v2
	v_sub_u32_e32 v1, v1, v3
	v_lshrrev_b32_e32 v3, 4, v1
	v_bitop3_b32 v1, v3, v1, 32 bitop3:0x6c
	v_ashrrev_i32_e32 v3, 31, v1
	v_lshrrev_b32_e32 v3, 26, v3
	v_add_u32_e32 v3, v1, v3
	v_lshlrev_b32_e32 v5, 3, v2
	v_ashrrev_i32_e32 v4, 6, v3
	v_and_b32_e32 v5, -16, v5
	v_lshlrev_b32_e32 v2, 5, v2
	v_add_u32_e32 v5, v4, v5
	v_and_b32_e32 v13, 32, v2
	v_and_b32_e32 v2, 0xc0, v3
	v_and_b32_e32 v4, 3, v4
	s_mov_b32 s14, 0x7fffffe0
	v_lshrrev_b32_e32 v6, 2, v5
	v_lshlrev_b32_e32 v7, 1, v5
	v_sub_u32_e32 v1, v1, v2
	v_and_or_b32 v4, v5, s14, v4
	v_and_b32_e32 v6, 4, v6
	v_and_b32_e32 v7, 24, v7
	v_ashrrev_i16_sdwa v1, v205, sext(v1) dst_sel:DWORD dst_unused:UNUSED_PAD src0_sel:DWORD src1_sel:BYTE_0
	v_or3_b32 v4, v4, v6, v7
	v_bfe_i32 v14, v1, 0, 16
	v_mul_lo_u32 v4, v4, s16
	v_add_u32_e32 v1, v13, v14
	v_mul_lo_u32 v15, v5, s16
	v_add_lshl_u32 v132, v4, v1, 1
	v_add_lshl_u32 v134, v1, v15, 1
	v_bfe_i32 v1, v12, 27, 1
	v_lshrrev_b32_e32 v1, 22, v1
	v_add_u32_e32 v1, v0, v1
	v_and_b32_e32 v1, 0xfffffc00, v1
	v_sub_u32_e32 v0, v0, v1
	v_lshrrev_b32_e32 v1, 4, v0
	v_ashrrev_i32_e32 v3, 31, v12
	s_add_u32 s4, s0, 0xc00000
	v_readlane_b32 s6, v253, 54
	v_bitop3_b32 v0, v1, v0, 32 bitop3:0x6c
	v_lshrrev_b32_e32 v3, 26, v3
	s_addc_u32 s33, s1, 0
	s_mul_i32 s6, s6, 0xb00000
	v_ashrrev_i32_e32 v1, 31, v0
	v_add_u32_e32 v3, v12, v3
	v_readlane_b32 s7, v253, 55
	s_add_u32 s6, s0, s6
	v_lshrrev_b32_e32 v1, 26, v1
	v_ashrrev_i32_e32 v3, 6, v3
	s_addc_u32 s7, s1, 0
	v_add_u32_e32 v1, v0, v1
	v_lshlrev_b32_e32 v4, 3, v3
	s_add_u32 s34, s6, 0x8740000
	v_ashrrev_i32_e32 v2, 6, v1
	v_and_b32_e32 v4, -16, v4
	s_addc_u32 s35, s7, 0
	s_ashr_i32 s17, s16, 31
	v_add_u32_e32 v4, v2, v4
	v_and_b32_e32 v2, 3, v2
	s_lshl_b64 s[8:9], s[16:17], 9
	v_and_or_b32 v2, v4, s14, v2
	v_readlane_b32 s14, v254, 52
	v_readlane_b32 s19, v255, 6
	s_mul_i32 s14, s8, s14
	s_mul_hi_u32 s15, s8, s19
	s_add_i32 s18, s15, s14
	s_lshr_b64 s[14:15], s[16:17], 23
	v_readlane_b32 s22, v254, 47
	s_mul_i32 s15, s14, s19
	v_readlane_b32 s23, v254, 48
	v_and_b32_e32 v1, 0xc0, v1
	s_add_i32 s18, s18, s15
	s_mul_i32 s15, s8, s23
	s_mul_hi_u32 s21, s8, s22
	s_ashr_i32 s20, s10, 6
	v_lshrrev_b32_e32 v5, 2, v4
	v_lshlrev_b32_e32 v6, 1, v4
	v_sub_u32_e32 v0, v0, v1
	s_add_i32 s15, s21, s15
	s_mul_i32 s14, s14, s22
	s_ashr_i32 s11, s10, 8
	s_lshl_b64 s[6:7], s[16:17], 8
	s_lshl_b32 s36, s20, 10
	v_and_b32_e32 v5, 4, v5
	v_and_b32_e32 v6, 24, v6
	v_lshlrev_b32_e32 v3, 5, v3
	v_ashrrev_i16_sdwa v0, v205, sext(v0) dst_sel:DWORD dst_unused:UNUSED_PAD src0_sel:DWORD src1_sel:BYTE_0
	s_add_i32 s15, s15, s14
	s_mul_i32 s14, s8, s22
	v_or3_b32 v2, v2, v5, v6
	v_and_b32_e32 v16, 32, v3
	v_bfe_i32 v17, v0, 0, 16
	s_add_u32 s30, s34, s14
	v_mul_lo_u32 v2, v2, s16
	v_add_u32_e32 v0, v16, v17
	s_addc_u32 s31, s35, s15
	s_add_i32 s37, s36, 0
	v_add_lshl_u32 v180, v2, v0, 1
	s_add_i32 m0, s37, 0x10000
	s_mul_i32 s19, s8, s19
	global_load_lds_dwordx4 v180, s[30:31]
	s_add_i32 m0, s37, 0x12000
	s_add_u32 s14, s30, s6
	global_load_lds_dwordx4 v132, s[30:31]
	s_addc_u32 s15, s31, s7
	s_add_i32 m0, s37, 0x14000
	v_mul_lo_u32 v18, v4, s16
	global_load_lds_dwordx4 v180, s[14:15]
	s_add_i32 m0, s37, 0x16000
	s_add_u32 s28, s4, s19
	v_mov_b32_e32 v133, v181
	s_addc_u32 s29, s33, s18
	s_add_i32 s38, s37, 0x2000
	v_add_lshl_u32 v136, v0, v18, 1
	v_lshl_add_u64 v[4:5], s[14:15], 0, v[180:181]
	v_lshl_add_u64 v[6:7], s[14:15], 0, v[132:133]
	global_load_lds_dwordx4 v132, s[14:15]
	s_mov_b32 m0, s37
	s_add_u32 s14, s28, s6
	global_load_lds_dwordx4 v136, s[28:29]
	s_mov_b32 m0, s38
	s_addc_u32 s15, s29, s7
	s_add_i32 s39, s37, 0x4000
	global_load_lds_dwordx4 v134, s[28:29]
	s_mov_b32 m0, s39
	s_add_i32 s46, s37, 0x6000
	global_load_lds_dwordx4 v136, s[14:15]
	s_mov_b32 m0, s46
	v_mov_b32_e32 v137, v181
	global_load_lds_dwordx4 v134, s[14:15]
	v_mov_b32_e32 v135, v181
	s_cmp_eq_u32 s11, 1
	v_lshl_add_u64 v[0:1], s[30:31], 0, v[180:181]
	v_lshl_add_u64 v[2:3], s[30:31], 0, v[132:133]
	v_lshl_add_u64 v[8:9], s[28:29], 0, v[136:137]
	v_lshl_add_u64 v[10:11], s[28:29], 0, v[134:135]
	s_cselect_b64 s[14:15], -1, 0
	s_cmp_lg_u32 s11, 1
	s_cbranch_scc1 .LBB0_1131
	s_barrier

.LBB0_1205:
	s_or_b64 exec, exec, s[8:9]
.LBB0_1206:
	s_or_b64 exec, exec, s[0:1]
	v_readlane_b32 s16, v253, 32
	v_readlane_b32 s18, v253, 34
	v_readlane_b32 s30, v253, 46
	v_readlane_b32 s31, v253, 47
	v_readlane_b32 s6, v255, 20
	s_mov_b64 s[0:1], s[30:31]
	s_movk_i32 s18, 0xb00
	v_mov_b32_e32 v18, v218
	v_readlane_b32 s7, v255, 21
	s_waitcnt lgkmcnt(0)
	s_barrier
	s_and_b64 vcc, exec, s[6:7]
	v_readfirstlane_b32 s10, v18
	v_readlane_b32 s17, v253, 33
	v_readlane_b32 s19, v253, 35
	v_readlane_b32 s20, v253, 36
	v_readlane_b32 s21, v253, 37
	v_readlane_b32 s22, v253, 38
	v_readlane_b32 s23, v253, 39
	v_readlane_b32 s24, v253, 40
	v_readlane_b32 s25, v253, 41
	v_readlane_b32 s26, v253, 42
	v_readlane_b32 s27, v253, 43
	v_readlane_b32 s28, v253, 44
	v_readlane_b32 s29, v253, 45
	s_cbranch_vccnz .LBB0_1248
	v_lshlrev_b32_e32 v0, 4, v18
	v_add_u32_e32 v1, 0x2000, v0
	v_ashrrev_i32_e32 v2, 31, v1
	v_lshrrev_b32_e32 v2, 22, v2
	v_add_u32_e32 v2, v1, v2
	v_ashrrev_i32_e32 v2, 10, v2
	v_mul_i32_i24_e32 v3, 0x400, v2
	v_sub_u32_e32 v1, v1, v3
	v_lshrrev_b32_e32 v3, 4, v1
	v_bitop3_b32 v1, v3, v1, 32 bitop3:0x6c
	v_ashrrev_i32_e32 v3, 31, v1
	v_lshrrev_b32_e32 v3, 26, v3
	v_add_u32_e32 v3, v1, v3
	v_lshlrev_b32_e32 v5, 3, v2
	v_ashrrev_i32_e32 v4, 6, v3
	v_and_b32_e32 v5, -16, v5
	v_lshlrev_b32_e32 v2, 5, v2
	v_add_u32_e32 v5, v4, v5
	v_and_b32_e32 v12, 32, v2
	v_and_b32_e32 v2, 0xc0, v3
	v_and_b32_e32 v4, 3, v4
	s_mov_b32 s14, 0x7fffffe0
	v_lshrrev_b32_e32 v6, 2, v5
	v_lshlrev_b32_e32 v7, 1, v5
	v_sub_u32_e32 v1, v1, v2
	v_and_or_b32 v4, v5, s14, v4
	v_and_b32_e32 v6, 4, v6
	v_and_b32_e32 v7, 24, v7
	v_ashrrev_i16_sdwa v1, v205, sext(v1) dst_sel:DWORD dst_unused:UNUSED_PAD src0_sel:DWORD src1_sel:BYTE_0
	v_or3_b32 v4, v4, v6, v7
	v_bfe_i32 v13, v1, 0, 16
	v_mul_lo_u32 v4, v4, s18
	v_add_u32_e32 v1, v12, v13
	v_mul_lo_u32 v14, v5, s18
	v_add_lshl_u32 v156, v4, v1, 1
	v_add_lshl_u32 v158, v1, v14, 1
	v_bfe_i32 v1, v18, 27, 1
	v_lshrrev_b32_e32 v1, 22, v1
	v_add_u32_e32 v1, v0, v1
	v_and_b32_e32 v1, 0xfffffc00, v1
	v_sub_u32_e32 v0, v0, v1
	v_lshrrev_b32_e32 v1, 4, v0
	v_ashrrev_i32_e32 v3, 31, v18
	s_add_u32 s4, s0, 0x12d00000
	v_readlane_b32 s6, v253, 54
	v_bitop3_b32 v0, v1, v0, 32 bitop3:0x6c
	v_lshrrev_b32_e32 v3, 26, v3
	s_addc_u32 s30, s1, 0
	s_mul_i32 s6, s6, 0x580000
	v_ashrrev_i32_e32 v1, 31, v0
	v_add_u32_e32 v3, v18, v3
	v_readlane_b32 s7, v253, 55
	s_add_u32 s6, s0, s6
	v_lshrrev_b32_e32 v1, 26, v1
	v_ashrrev_i32_e32 v3, 6, v3
	s_addc_u32 s7, s1, 0
	v_add_u32_e32 v1, v0, v1
	v_lshlrev_b32_e32 v4, 3, v3
	s_add_u32 s31, s6, 0x9d40000
	v_ashrrev_i32_e32 v2, 6, v1
	v_and_b32_e32 v4, -16, v4
	s_addc_u32 s33, s7, 0
	s_ashr_i32 s19, s18, 31
	v_add_u32_e32 v4, v2, v4
	v_and_b32_e32 v2, 3, v2
	s_lshl_b64 s[8:9], s[18:19], 9
	v_and_or_b32 v2, v4, s14, v2
	v_readlane_b32 s14, v254, 53
	s_mul_i32 s14, s8, s14
	s_mul_hi_u32 s15, s8, s95
	s_add_i32 s16, s15, s14
	s_lshr_b64 s[14:15], s[18:19], 23
	v_readlane_b32 s22, v254, 50
	s_mul_i32 s15, s14, s95
	v_readlane_b32 s23, v254, 51
	v_and_b32_e32 v1, 0xc0, v1
	s_add_i32 s16, s16, s15
	s_mul_i32 s15, s8, s23
	s_mul_hi_u32 s21, s8, s22
	s_ashr_i32 s20, s10, 6
	v_lshrrev_b32_e32 v5, 2, v4
	v_lshlrev_b32_e32 v6, 1, v4
	v_sub_u32_e32 v0, v0, v1
	s_add_i32 s15, s21, s15
	s_mul_i32 s14, s14, s22
	s_ashr_i32 s11, s10, 8
	s_lshl_b64 s[6:7], s[18:19], 8
	s_lshl_b32 s34, s20, 10
	v_and_b32_e32 v5, 4, v5
	v_and_b32_e32 v6, 24, v6
	v_lshlrev_b32_e32 v3, 5, v3
	v_ashrrev_i16_sdwa v0, v205, sext(v0) dst_sel:DWORD dst_unused:UNUSED_PAD src0_sel:DWORD src1_sel:BYTE_0
	s_add_i32 s15, s15, s14
	s_mul_i32 s14, s8, s22
	v_or3_b32 v2, v2, v5, v6
	v_and_b32_e32 v15, 32, v3
	v_bfe_i32 v16, v0, 0, 16
	s_add_u32 s28, s31, s14
	v_mul_lo_u32 v2, v2, s18
	v_add_u32_e32 v0, v15, v16
	s_addc_u32 s29, s33, s15
	s_add_i32 s35, s34, 0
	v_add_lshl_u32 v180, v2, v0, 1
	s_add_i32 m0, s35, 0x10000
	s_mul_i32 s17, s8, s95
	global_load_lds_dwordx4 v180, s[28:29]
	s_add_i32 m0, s35, 0x12000
	s_add_u32 s14, s28, s6
	global_load_lds_dwordx4 v156, s[28:29]
	s_addc_u32 s15, s29, s7
	s_add_i32 m0, s35, 0x14000
	v_mul_lo_u32 v17, v4, s18
	global_load_lds_dwordx4 v180, s[14:15]
	s_add_i32 m0, s35, 0x16000
	s_add_u32 s26, s4, s17
	v_mov_b32_e32 v157, v181
	s_addc_u32 s27, s30, s16
	s_add_i32 s36, s35, 0x2000
	s_waitcnt vmcnt(0)
	v_add_lshl_u32 v160, v0, v17, 1
	v_lshl_add_u64 v[4:5], s[14:15], 0, v[180:181]
	v_lshl_add_u64 v[6:7], s[14:15], 0, v[156:157]
	global_load_lds_dwordx4 v156, s[14:15]
	s_mov_b32 m0, s35
	s_add_u32 s14, s26, s6
	global_load_lds_dwordx4 v160, s[26:27]
	s_mov_b32 m0, s36
	s_addc_u32 s15, s27, s7
	s_add_i32 s37, s35, 0x4000
	global_load_lds_dwordx4 v158, s[26:27]
	s_mov_b32 m0, s37
	s_add_i32 s38, s35, 0x6000
	global_load_lds_dwordx4 v160, s[14:15]
	s_mov_b32 m0, s38
	v_mov_b32_e32 v161, v181
	global_load_lds_dwordx4 v158, s[14:15]
	v_mov_b32_e32 v159, v181
	s_cmp_eq_u32 s11, 1
	v_mov_b32_e32 v240, 1
	v_lshl_add_u64 v[0:1], s[28:29], 0, v[180:181]
	v_lshl_add_u64 v[2:3], s[28:29], 0, v[156:157]
	v_lshl_add_u64 v[8:9], s[26:27], 0, v[160:161]
	v_lshl_add_u64 v[10:11], s[26:27], 0, v[158:159]
	s_cselect_b64 s[14:15], -1, 0
	s_cmp_lg_u32 s11, 1
	s_cbranch_scc1 .LBB0_1209
	s_barrier
